# prologue x->bf16 loop: software prefetch one iteration ahead (second register set + copy, counted vmcnt), on v53
# baseline (speedup 1.0000x reference)
; __device__ __forceinline__ float wave_sum(float v) {
; #pragma unroll
;     for (int o = 1; o < 64; o <<= 1) v += __shfl_xor(v, o);
;     return v;
; __device__ __forceinline__ void prologue(const Params& P, LAS unsigned char* lds, int wave) {
;     ...
;     { const float* x = P.in[0]; bf16_t* hb = (bf16_t*)(ws + WS_HBA); float* sq = (float*)(ws + WS_SSQ);
; #pragma unroll 1
;       for (int r = 2 * gw; r < MT; r += 2 * NGW) {
;           const f32x4* xr = (const f32x4*)(x + (size_t)r * 1024) + lane; f32x4 v[8]; float s0 = 0.f, s1 = 0.f;
; #pragma unroll
;           for (int j = 0; j < 8; ++j) v[j] = __builtin_nontemporal_load(xr + 64 * j);
.LBB0_87:
	s_or_b64 exec, exec, s[4:5]
	s_cmpk_gt_i32 s87, 0x3fff
	v_mbcnt_lo_u32_b32 v244, -1, 0
	s_cbranch_scc1 .LBB0_92
	v_mbcnt_hi_u32_b32 v2, -1, v244
	v_and_b32_e32 v3, 64, v2
	v_add_u32_e32 v3, 64, v3
	v_xor_b32_e32 v4, 1, v2
	v_cmp_lt_i32_e32 vcc, v4, v3
	s_lshl_b32 s4, s87, 1
	s_lshl_b32 s6, s56, 4
	v_cndmask_b32_e32 v4, v2, v4, vcc
	v_lshlrev_b32_e32 v44, 2, v4
	v_xor_b32_e32 v4, 2, v2
	v_cmp_lt_i32_e32 vcc, v4, v3
	s_ashr_i32 s5, s4, 31
	s_ashr_i32 s7, s6, 31
	v_cndmask_b32_e32 v4, v2, v4, vcc
	v_lshlrev_b32_e32 v45, 2, v4
	v_xor_b32_e32 v4, 4, v2
	v_cmp_lt_i32_e32 vcc, v4, v3
	s_lshl_b64 s[8:9], s[4:5], 2
	s_lshl_b64 s[10:11], s[6:7], 2
	v_cndmask_b32_e32 v4, v2, v4, vcc
	v_lshlrev_b32_e32 v46, 2, v4
	v_xor_b32_e32 v4, 8, v2
	v_cmp_lt_i32_e32 vcc, v4, v3
	s_lshl_b64 s[20:21], s[4:5], 12
	s_add_u32 s16, s16, s20
	v_cndmask_b32_e32 v4, v2, v4, vcc
	v_lshlrev_b32_e32 v47, 2, v4
	v_xor_b32_e32 v4, 16, v2
	v_cmp_lt_i32_e32 vcc, v4, v3
	v_ashrrev_i32_e32 v71, 31, v70
	s_addc_u32 s17, s17, s21
	v_cndmask_b32_e32 v4, v2, v4, vcc
	v_lshlrev_b32_e32 v48, 2, v4
	v_xor_b32_e32 v4, 32, v2
	v_cmp_lt_i32_e32 vcc, v4, v3
	s_lshl_b64 s[20:21], s[4:5], 11
	v_cmp_eq_u32_e64 s[0:1], 0, v70
	v_cndmask_b32_e32 v2, v2, v4, vcc
	v_lshlrev_b32_e32 v49, 2, v2
	v_lshl_add_u64 v[2:3], v[70:71], 4, s[16:17]
	s_mov_b64 s[16:17], 0x1000
	v_lshl_add_u64 v[36:37], v[2:3], 0, s[16:17]
	s_lshl_b64 s[16:17], s[6:7], 12
	v_lshl_add_u64 v[38:39], v[70:71], 3, s[20:21]
	s_lshl_b64 s[20:21], s[6:7], 11
	global_load_dwordx4 v[128:131], v[36:37], off offset:-4096 nt
	global_load_dwordx4 v[112:115], v[36:37], off nt
	global_load_dwordx4 v[124:127], v[36:37], off offset:-3072 nt
	global_load_dwordx4 v[108:111], v[36:37], off offset:1024 nt
	global_load_dwordx4 v[120:123], v[36:37], off offset:-2048 nt
	global_load_dwordx4 v[104:107], v[36:37], off offset:2048 nt
	global_load_dwordx4 v[116:119], v[36:37], off offset:-1024 nt
	global_load_dwordx4 v[100:103], v[36:37], off offset:3072 nt
	s_waitcnt vmcnt(0)
	s_branch .Lx_entry

; __device__ __forceinline__ unsigned pk2(float lo, float hi) { return cvt_pk_bf16(lo, hi); }
; __device__ __forceinline__ void prologue(const Params& P, LAS unsigned char* lds, int wave) {
;     ...
;       for (int r = 2 * gw; r < MT; r += 2 * NGW) {
;           const f32x4* xr = (const f32x4*)(x + (size_t)r * 1024) + lane; f32x4 v[8]; float s0 = 0.f, s1 = 0.f;
; #pragma unroll
;           for (int j = 0; j < 8; ++j) v[j] = __builtin_nontemporal_load(xr + 64 * j);
; #pragma unroll
;           for (int j = 0; j < 4; ++j) { s0 += (v[j][0] * v[j][0] + v[j][1] * v[j][1]) + (v[j][2] * v[j][2] + v[j][3] * v[j][3]);
;               s1 += (v[4 + j][0] * v[4 + j][0] + v[4 + j][1] * v[4 + j][1]) + (v[4 + j][2] * v[4 + j][2] + v[4 + j][3] * v[4 + j][3]); }
;           s0 = wave_sum(s0); s1 = wave_sum(s1); if (lane == 0) { sq[r] = s0; sq[r + 1] = s1; }
;           u32x2* o = (u32x2*)(hb + (size_t)r * 1024) + lane;
; #pragma unroll
;           for (int j = 0; j < 8; ++j) { u32x2 w; w.x = pk2(v[j][0], v[j][1]); w.y = pk2(v[j][2], v[j][3]); o[64 * j] = w; }
.LBB0_90:
	s_waitcnt vmcnt(8)
.Lx_entry:
	s_waitcnt lgkmcnt(0)
	v_mov_b64_e32 v[2:3], v[100:101]
	v_mov_b64_e32 v[4:5], v[102:103]
	v_mov_b64_e32 v[6:7], v[104:105]
	v_mov_b64_e32 v[8:9], v[106:107]
	v_mov_b64_e32 v[10:11], v[108:109]
	v_mov_b64_e32 v[12:13], v[110:111]
	v_mov_b64_e32 v[14:15], v[112:113]
	v_mov_b64_e32 v[16:17], v[114:115]
	v_mov_b64_e32 v[18:19], v[116:117]
	v_mov_b64_e32 v[20:21], v[118:119]
	v_mov_b64_e32 v[22:23], v[120:121]
	v_mov_b64_e32 v[24:25], v[122:123]
	v_mov_b64_e32 v[26:27], v[124:125]
	v_mov_b64_e32 v[28:29], v[126:127]
	v_mov_b64_e32 v[30:31], v[128:129]
	v_mov_b64_e32 v[32:33], v[130:131]
	s_add_i32 s28, s4, s6
	s_cmpk_gt_i32 s28, 0x7fff
	s_cbranch_scc1 .Lx_nopf
	v_lshl_add_u64 v[132:133], v[36:37], 0, s[16:17]
	global_load_dwordx4 v[128:131], v[132:133], off offset:-4096 nt
	global_load_dwordx4 v[112:115], v[132:133], off nt
	global_load_dwordx4 v[124:127], v[132:133], off offset:-3072 nt
	global_load_dwordx4 v[108:111], v[132:133], off offset:1024 nt
	global_load_dwordx4 v[120:123], v[132:133], off offset:-2048 nt
	global_load_dwordx4 v[104:107], v[132:133], off offset:2048 nt
	global_load_dwordx4 v[116:119], v[132:133], off offset:-1024 nt
	global_load_dwordx4 v[100:103], v[132:133], off offset:3072 nt
.Lx_nopf:
	v_mov_b32_e32 v42, v31
	v_mov_b32_e32 v43, v15
	v_mov_b32_e32 v52, v33
	v_mov_b32_e32 v53, v17
	v_mov_b32_e32 v56, v27
	v_mov_b32_e32 v57, v11
	v_mov_b32_e32 v60, v29
	v_mov_b32_e32 v61, v13
	v_mov_b32_e32 v40, v30
	v_mov_b32_e32 v41, v14
	v_mov_b32_e32 v50, v32
	v_mov_b32_e32 v51, v16
	v_mov_b32_e32 v54, v26
	v_mov_b32_e32 v55, v10
	v_mov_b32_e32 v58, v28
	v_mov_b32_e32 v59, v12
	v_mov_b32_e32 v64, v23
	v_mov_b32_e32 v65, v7
	v_mov_b32_e32 v68, v25
	v_mov_b32_e32 v69, v9
	v_pk_mul_f32 v[42:43], v[42:43], v[42:43]
	v_pk_mul_f32 v[52:53], v[52:53], v[52:53]
	v_pk_mul_f32 v[56:57], v[56:57], v[56:57]
	v_pk_mul_f32 v[60:61], v[60:61], v[60:61]
	v_mov_b32_e32 v62, v22
	v_mov_b32_e32 v63, v6
	v_mov_b32_e32 v66, v24
	v_mov_b32_e32 v67, v8
	v_mov_b32_e32 v72, v19
	v_mov_b32_e32 v73, v3
	v_mov_b32_e32 v76, v21
	v_mov_b32_e32 v77, v5
	v_pk_mul_f32 v[64:65], v[64:65], v[64:65]
	v_pk_mul_f32 v[68:69], v[68:69], v[68:69]
	v_pk_fma_f32 v[40:41], v[40:41], v[40:41], v[42:43]
	v_pk_fma_f32 v[42:43], v[50:51], v[50:51], v[52:53]
	v_pk_fma_f32 v[50:51], v[54:55], v[54:55], v[56:57]
	v_pk_fma_f32 v[52:53], v[58:59], v[58:59], v[60:61]
	v_mov_b32_e32 v70, v18
	v_mov_b32_e32 v71, v2
	v_mov_b32_e32 v74, v20
	v_mov_b32_e32 v75, v4
	v_pk_mul_f32 v[72:73], v[72:73], v[72:73]
	v_pk_mul_f32 v[76:77], v[76:77], v[76:77]
	v_pk_fma_f32 v[54:55], v[62:63], v[62:63], v[64:65]
	v_pk_fma_f32 v[56:57], v[66:67], v[66:67], v[68:69]
	v_pk_add_f32 v[40:41], v[40:41], v[42:43]
	v_pk_add_f32 v[42:43], v[50:51], v[52:53]
	v_pk_fma_f32 v[58:59], v[70:71], v[70:71], v[72:73]
	v_pk_fma_f32 v[60:61], v[74:75], v[74:75], v[76:77]
	v_pk_add_f32 v[50:51], v[54:55], v[56:57]
	v_pk_add_f32 v[40:41], v[40:41], v[42:43]
	v_pk_add_f32 v[52:53], v[58:59], v[60:61]
	v_pk_add_f32 v[40:41], v[40:41], v[50:51]
	s_nop 0
	v_pk_add_f32 v[40:41], v[40:41], v[52:53]
	ds_bpermute_b32 v42, v44, v40
	ds_bpermute_b32 v43, v44, v41
	s_waitcnt lgkmcnt(0)
	v_pk_add_f32 v[40:41], v[40:41], v[42:43]
	ds_bpermute_b32 v42, v45, v40
	ds_bpermute_b32 v43, v45, v41
	s_waitcnt lgkmcnt(0)
	v_pk_add_f32 v[40:41], v[40:41], v[42:43]
	ds_bpermute_b32 v42, v46, v40
	ds_bpermute_b32 v43, v46, v41
	s_waitcnt lgkmcnt(0)
	v_pk_add_f32 v[40:41], v[40:41], v[42:43]
	ds_bpermute_b32 v42, v47, v40
	ds_bpermute_b32 v43, v47, v41
	s_waitcnt lgkmcnt(0)
	v_pk_add_f32 v[40:41], v[40:41], v[42:43]
	ds_bpermute_b32 v42, v48, v40
	ds_bpermute_b32 v43, v48, v41
	s_waitcnt lgkmcnt(0)
	v_pk_add_f32 v[40:41], v[40:41], v[42:43]
	ds_bpermute_b32 v42, v49, v40
	ds_bpermute_b32 v43, v49, v41
	s_and_saveexec_b64 s[22:23], s[0:1]
	s_cbranch_execz .LBB0_89
	s_add_u32 s26, s54, s8
	s_addc_u32 s27, s55, s9
	s_waitcnt lgkmcnt(0)
	v_pk_add_f32 v[40:41], v[40:41], v[42:43]
	v_mov_b64_e32 v[42:43], s[26:27]
	flat_store_dwordx2 v[42:43], v[40:41]
	s_branch .LBB0_89
